# sample-attn loop: + full-lane key-norm rsqrt chain, fp8 tile store in last MFMA gap, first key-norm operand reads hoisted above exp, PV / rope-sum LDS reads prefetched
# speedup vs baseline: 1.0049x; 1.0049x over previous
.LBB0_1608:
	ds_read_b128 v[16:19], v214 offset:512
	ds_read_b128 v[20:23], v214 offset:528
	s_waitcnt lgkmcnt(1)
	v_lshlrev_b32_e32 v24, 16, v16
	v_and_b32_e32 v16, 0xffff0000, v16
	v_mul_f32_e32 v16, v16, v16
	v_lshlrev_b32_e32 v25, 16, v17
	v_fmac_f32_e32 v16, v24, v24
	v_and_b32_e32 v17, 0xffff0000, v17
	v_fmac_f32_e32 v16, v25, v25
	v_lshlrev_b32_e32 v26, 16, v18
	v_fmac_f32_e32 v16, v17, v17
	v_and_b32_e32 v18, 0xffff0000, v18
	v_fmac_f32_e32 v16, v26, v26
	v_lshlrev_b32_e32 v27, 16, v19
	v_fmac_f32_e32 v16, v18, v18
	v_and_b32_e32 v19, 0xffff0000, v19
	v_fmac_f32_e32 v16, v27, v27
	v_fmac_f32_e32 v16, v19, v19
	s_waitcnt lgkmcnt(0)
	v_lshlrev_b32_e32 v17, 16, v20
	v_and_b32_e32 v18, 0xffff0000, v20
	v_fmac_f32_e32 v16, v17, v17
	v_lshlrev_b32_e32 v19, 16, v21
	v_fmac_f32_e32 v16, v18, v18
	v_and_b32_e32 v20, 0xffff0000, v21
	v_fmac_f32_e32 v16, v19, v19
	v_lshlrev_b32_e32 v21, 16, v22
	v_fmac_f32_e32 v16, v20, v20
	v_fmac_f32_e32 v16, v21, v21
	ds_read_b128 v[18:21], v214 offset:19456
	v_and_b32_e32 v22, 0xffff0000, v22
	v_lshlrev_b32_e32 v24, 16, v23
	v_fmac_f32_e32 v16, v22, v22
	v_and_b32_e32 v23, 0xffff0000, v23
	v_fmac_f32_e32 v16, v24, v24
	v_fmac_f32_e32 v16, v23, v23
	ds_read_b128 v[22:25], v214 offset:19472
	s_waitcnt lgkmcnt(1)
	v_and_b32_e32 v17, 0xffff0000, v18
	v_lshlrev_b32_e32 v26, 16, v18
	v_mul_f32_e32 v17, v17, v17
	v_lshlrev_b32_e32 v18, 16, v19
	v_fmac_f32_e32 v17, v26, v26
	v_and_b32_e32 v19, 0xffff0000, v19
	v_fmac_f32_e32 v17, v18, v18
	v_lshlrev_b32_e32 v27, 16, v20
	v_fmac_f32_e32 v17, v19, v19
	v_and_b32_e32 v20, 0xffff0000, v20
	v_fmac_f32_e32 v17, v27, v27
	v_lshlrev_b32_e32 v28, 16, v21
	v_fmac_f32_e32 v17, v20, v20
	v_and_b32_e32 v21, 0xffff0000, v21
	v_fmac_f32_e32 v17, v28, v28
	v_fmac_f32_e32 v17, v21, v21
	s_waitcnt lgkmcnt(0)
	v_lshlrev_b32_e32 v18, 16, v22
	v_and_b32_e32 v19, 0xffff0000, v22
	v_fmac_f32_e32 v17, v18, v18
	v_lshlrev_b32_e32 v20, 16, v23
	v_fmac_f32_e32 v17, v19, v19
	v_and_b32_e32 v21, 0xffff0000, v23
	v_fmac_f32_e32 v17, v20, v20
	v_lshlrev_b32_e32 v22, 16, v24
	v_fmac_f32_e32 v17, v21, v21
	v_and_b32_e32 v23, 0xffff0000, v24
	v_fmac_f32_e32 v17, v22, v22
	v_lshlrev_b32_e32 v24, 16, v25
	v_fmac_f32_e32 v17, v23, v23
	v_and_b32_e32 v25, 0xffff0000, v25
	v_fmac_f32_e32 v17, v24, v24
	v_fmac_f32_e32 v17, v25, v25
	v_fmac_f32_e32 v16, 0x3b800000, v180
	v_fmac_f32_e32 v17, 0x3b800000, v229
	ds_bpermute_b32 v19, v199, v16
	ds_bpermute_b32 v18, v199, v17
	s_waitcnt lgkmcnt(0)
	v_add_f32_e32 v16, v16, v19
	v_add_f32_e32 v17, v17, v18
	v_cndmask_b32_e64 v16, v17, v16, s[6:7]
	v_fmamk_f32 v16, v16, 0x3c2aaaab, v209
	v_mul_f32_e32 v19, 0x4f800000, v16
	v_cmp_gt_f32_e32 vcc, s37, v16
	s_nop 1
	v_cndmask_b32_e32 v16, v16, v19, vcc
	v_sqrt_f32_e32 v19, v16
	s_nop 0
	v_add_u32_e32 v20, -1, v19
	v_fma_f32 v22, -v20, v19, v16
	v_add_u32_e32 v21, 1, v19
	v_cmp_ge_f32_e64 s[0:1], 0, v22
	s_nop 1
	v_cndmask_b32_e64 v20, v19, v20, s[0:1]
	v_fma_f32 v19, -v21, v19, v16
	v_cmp_lt_f32_e64 s[0:1], 0, v19
	s_nop 1
	v_cndmask_b32_e64 v19, v20, v21, s[0:1]
	v_mul_f32_e32 v20, 0x37800000, v19
	v_cndmask_b32_e32 v19, v19, v20, vcc
	v_cmp_class_f32_e32 vcc, v16, v210
	s_nop 1
	v_cndmask_b32_e32 v16, v19, v16, vcc
	v_div_scale_f32 v19, s[0:1], v16, v16, 1.0
	v_rcp_f32_e32 v20, v19
	s_nop 0
	v_fma_f32 v18, -v19, v20, 1.0
	v_fmac_f32_e32 v20, v18, v20
	v_div_scale_f32 v18, vcc, 1.0, v16, 1.0
	v_mul_f32_e32 v21, v18, v20
	v_fma_f32 v23, -v19, v21, v18
	v_fmac_f32_e32 v21, v23, v20
	v_fma_f32 v18, -v19, v21, v18
	s_nop 0
	v_div_fmas_f32 v18, v18, v20, v21
	v_div_fixup_f32 v16, v18, v16, 1.0
	ds_write_b32 v203, v16
.LBB0_1610:
	s_waitcnt lgkmcnt(0)
	ds_read_b128 v[16:19], v215
	ds_read_b128 v[20:23], v216
	ds_read_b128 v[24:27], v215 offset:64
	ds_read_b128 v[28:31], v216 offset:64
	ds_read_b128 v[190:193], v215 offset:512
	s_add_i32 s43, s42, 1
	s_waitcnt lgkmcnt(3)
	v_mfma_f32_16x16x32_bf16 v[16:19], v[16:19], v[20:23], 0
	ds_read_b128 v[20:23], v215 offset:128
	ds_read_b128 v[230:233], v216 offset:128
	s_cmp_ge_u32 s43, s39
	s_waitcnt lgkmcnt(3)
	v_mfma_f32_16x16x32_bf16 v[16:19], v[24:27], v[28:31], v[16:19]
	ds_read_b128 v[24:27], v215 offset:192
	ds_read_b128 v[28:31], v216 offset:192
	s_waitcnt lgkmcnt(2)
	v_mfma_f32_16x16x32_bf16 v[16:19], v[20:23], v[230:233], v[16:19]
	ds_read_b128 v[20:23], v215 offset:256
	ds_read_b128 v[230:233], v216 offset:256
	s_waitcnt lgkmcnt(2)
	v_mfma_f32_16x16x32_bf16 v[16:19], v[24:27], v[28:31], v[16:19]
	ds_read_b128 v[24:27], v215 offset:320
	ds_read_b128 v[28:31], v216 offset:320
	s_waitcnt lgkmcnt(2)
	v_mfma_f32_16x16x32_bf16 v[16:19], v[20:23], v[230:233], v[16:19]
	ds_read_b128 v[20:23], v215 offset:384
	ds_read_b128 v[230:233], v216 offset:384
	s_waitcnt lgkmcnt(2)
	v_mfma_f32_16x16x32_bf16 v[16:19], v[24:27], v[28:31], v[16:19]
	ds_read_b128 v[24:27], v215 offset:448
	ds_read_b128 v[28:31], v216 offset:448
	ds_read_b128 v[234:237], v216 offset:512
	s_waitcnt lgkmcnt(0)
	s_barrier
	v_mfma_f32_16x16x32_bf16 v[16:19], v[20:23], v[230:233], v[16:19]
	ds_read_b32 v20, v217
	v_mfma_f32_16x16x32_bf16 v[16:19], v[24:27], v[28:31], v[16:19]
	v_mfma_f32_16x16x32_bf16 v[16:19], v[190:193], v[234:237], v[16:19]
	ds_read_b128 v[246:249], v211
	ds_read_b128 v[250:253], v211 offset:16
	ds_read_b128 v[24:27], v211 offset:64
	ds_read_b128 v[28:31], v211 offset:80
	s_waitcnt lgkmcnt(4)
	s_nop 6
	v_fma_f32 v16, v16, v20, -v177
	v_fma_f32 v17, v17, v20, -v177
	v_fma_f32 v18, v18, v20, -v177
	v_fma_f32 v19, v19, v20, -v177
	v_exp_f32_e32 v192, v16
	v_exp_f32_e32 v193, v17
	v_exp_f32_e32 v190, v18
	v_exp_f32_e32 v191, v19
	v_bfe_u32 v16, v192, 16, 1
	v_bfe_u32 v17, v193, 16, 1
	v_bfe_u32 v18, v190, 16, 1
	v_bfe_u32 v19, v191, 16, 1
	v_add3_u32 v16, v192, v16, s38
	v_add3_u32 v17, v193, v17, s38
	v_add3_u32 v18, v190, v18, s38
	v_add3_u32 v19, v191, v19, s38
	ds_write_b16_d16_hi v218, v16
	ds_write_b16_d16_hi v218, v17 offset:144
	ds_write_b16_d16_hi v218, v18 offset:288
	ds_write_b16_d16_hi v218, v19 offset:432
	s_cbranch_scc1 .LBB0_1613
	s_waitcnt lgkmcnt(6)
	v_mfma_scale_f32_32x32x64_f8f6f4 v[230:245], v[32:39], v[246:253], 0, v208, v208 op_sel_hi:[0,0,0]
	v_cvt_pk_bf16_f32 v16, v96, v97
	v_cvt_pk_bf16_f32 v17, v98, v99
	ds_write_b64 v201, v[16:17] offset:37888
	v_cvt_pk_bf16_f32 v18, v100, v101
	v_cvt_pk_bf16_f32 v19, v102, v103
	ds_write_b64 v201, v[18:19] offset:42624
	v_cvt_pk_bf16_f32 v20, v104, v105
	v_cvt_pk_bf16_f32 v21, v106, v107
	ds_write_b64 v201, v[20:21] offset:47360
	v_cvt_pk_bf16_f32 v22, v108, v109
	v_cvt_pk_bf16_f32 v23, v110, v111
	ds_write_b64 v201, v[22:23] offset:52096
	ds_read_b128 v[246:249], v211 offset:128
	ds_read_b128 v[250:253], v211 offset:144
	s_waitcnt lgkmcnt(10)
	v_mfma_scale_f32_32x32x64_f8f6f4 v[230:245], v[40:47], v[24:31], v[230:245], v208, v208 op_sel_hi:[0,0,0]
	v_cvt_pk_bf16_f32 v16, v112, v113
	v_cvt_pk_bf16_f32 v17, v114, v115
	ds_write_b64 v201, v[16:17] offset:56832
	v_cvt_pk_bf16_f32 v18, v116, v117
	v_cvt_pk_bf16_f32 v19, v118, v119
	ds_write_b64 v201, v[18:19] offset:61568
	v_cvt_pk_bf16_f32 v20, v120, v121
	v_cvt_pk_bf16_f32 v21, v122, v123
	ds_write_b64 v204, v[20:21] offset:28416
	v_cvt_pk_bf16_f32 v22, v124, v125
	v_cvt_pk_bf16_f32 v23, v126, v127
	ds_write_b64 v204, v[22:23] offset:33152
	v_cvt_pk_bf16_f32 v16, v128, v129
	v_cvt_pk_bf16_f32 v17, v130, v131
	ds_write_b64 v213, v[16:17] offset:38400
	ds_read_b128 v[24:27], v211 offset:192
	ds_read_b128 v[28:31], v211 offset:208
	s_waitcnt lgkmcnt(7)
	v_mfma_scale_f32_32x32x64_f8f6f4 v[230:245], v[48:55], v[246:253], v[230:245], v208, v208 op_sel_hi:[0,0,0]
	v_readlane_b32 s0, v227, s41
	s_ashr_i32 s1, s0, 31
	s_lshl_b64 s[0:1], s[0:1], 7
	s_or_b32 s0, s0, 64
	s_lshl_b64 s[2:3], s[0:1], 10
	v_lshl_add_u64 v[16:17], v[182:183], 0, s[2:3]
	v_add_co_u32_e32 v18, vcc, 0x2000, v16
	s_lshl_b64 s[0:1], s[0:1], 7
	s_nop 0
	v_addc_co_u32_e32 v19, vcc, 0, v17, vcc
	global_load_dwordx4 v[96:99], v[16:17], off nt
	global_load_dwordx4 v[100:103], v[18:19], off nt
	v_add_co_u32_e32 v18, vcc, 0x4000, v16
	s_nop 1
	v_addc_co_u32_e32 v19, vcc, 0, v17, vcc
	v_add_co_u32_e32 v20, vcc, 0x6000, v16
	s_nop 1
	v_addc_co_u32_e32 v21, vcc, 0, v17, vcc
	global_load_dwordx4 v[104:107], v[18:19], off nt
	ds_read_b128 v[246:249], v211
	ds_read_b128 v[250:253], v211 offset:16
	s_waitcnt lgkmcnt(2)
	v_mfma_scale_f32_32x32x64_f8f6f4 v[230:245], v[56:63], v[24:31], v[230:245], v208, v208 op_sel_hi:[0,0,0]
	global_load_dwordx4 v[108:111], v[20:21], off nt
	v_add_co_u32_e32 v18, vcc, 0x8000, v16
	s_nop 1
	v_addc_co_u32_e32 v19, vcc, 0, v17, vcc
	v_add_co_u32_e32 v20, vcc, 0xa000, v16
	s_nop 1
	v_addc_co_u32_e32 v21, vcc, 0, v17, vcc
	global_load_dwordx4 v[112:115], v[18:19], off nt
	global_load_dwordx4 v[116:119], v[20:21], off nt
	v_add_co_u32_e32 v18, vcc, 0xc000, v16
	s_nop 1
	v_addc_co_u32_e32 v19, vcc, 0, v17, vcc
	v_add_co_u32_e32 v16, vcc, 0xe000, v16
	s_nop 1
	v_addc_co_u32_e32 v17, vcc, 0, v17, vcc
	global_load_dwordx4 v[120:123], v[18:19], off nt
	global_load_dwordx4 v[124:127], v[16:17], off nt
	v_lshl_add_u64 v[16:17], v[184:185], 0, s[0:1]
	global_load_dwordx4 v[128:131], v[16:17], off nt
	ds_read_b128 v[24:27], v211 offset:64
	ds_read_b128 v[28:31], v211 offset:80
	v_mul_f32_e32 v180, v231, v231
	v_fmac_f32_e32 v180, v230, v230
	v_fmac_f32_e32 v180, v232, v232
	v_fmac_f32_e32 v180, v233, v233
	v_fmac_f32_e32 v180, v234, v234
	v_fmac_f32_e32 v180, v235, v235
	v_fmac_f32_e32 v180, v236, v236
	v_fmac_f32_e32 v180, v237, v237
	v_fmac_f32_e32 v180, v238, v238
	v_fmac_f32_e32 v180, v239, v239
	v_fmac_f32_e32 v180, v240, v240
	v_fmac_f32_e32 v180, v241, v241
	v_fmac_f32_e32 v180, v242, v242
	v_fmac_f32_e32 v180, v243, v243
	v_fmac_f32_e32 v180, v244, v244
	v_fmac_f32_e32 v180, v245, v245
	s_waitcnt lgkmcnt(2)
	v_mfma_scale_f32_32x32x64_f8f6f4 v[230:245], v[64:71], v[246:253], 0, v208, v208 op_sel_hi:[0,0,0]
	ds_read_b128 v[246:249], v211 offset:128
	ds_read_b128 v[250:253], v211 offset:144
	s_waitcnt lgkmcnt(2)
	v_mfma_scale_f32_32x32x64_f8f6f4 v[230:245], v[72:79], v[24:31], v[230:245], v208, v208 op_sel_hi:[0,0,0]
	ds_read_b128 v[24:27], v211 offset:192
	ds_read_b128 v[28:31], v211 offset:208
	s_waitcnt lgkmcnt(2)
	v_mfma_scale_f32_32x32x64_f8f6f4 v[230:245], v[80:87], v[246:253], v[230:245], v208, v208 op_sel_hi:[0,0,0]
	ds_read_b128 v[246:249], v211 offset:8704
	ds_read_b128 v[250:253], v211 offset:8720
	s_waitcnt lgkmcnt(2)
	v_mfma_scale_f32_32x32x64_f8f6f4 v[230:245], v[88:95], v[24:31], v[230:245], v208, v208 op_sel_hi:[0,0,0]
	ds_read_b128 v[24:27], v211 offset:8768
	ds_read_b128 v[28:31], v211 offset:8784
	s_nop 15
	s_nop 1
	v_fmac_f32_e32 v180, v230, v230
	v_fmac_f32_e32 v180, v231, v231
	v_fmac_f32_e32 v180, v232, v232
	v_fmac_f32_e32 v180, v233, v233
	v_fmac_f32_e32 v180, v234, v234
	v_fmac_f32_e32 v180, v235, v235
	v_fmac_f32_e32 v180, v236, v236
	v_fmac_f32_e32 v180, v237, v237
	v_fmac_f32_e32 v180, v238, v238
	v_fmac_f32_e32 v180, v239, v239
	v_fmac_f32_e32 v180, v240, v240
	v_fmac_f32_e32 v180, v241, v241
	v_fmac_f32_e32 v180, v242, v242
	v_fmac_f32_e32 v180, v243, v243
	v_fmac_f32_e32 v180, v244, v244
	v_fmac_f32_e32 v180, v245, v245
	s_waitcnt lgkmcnt(2)
	v_mfma_scale_f32_32x32x64_f8f6f4 v[230:245], v[32:39], v[246:253], 0, v208, v208 op_sel_hi:[0,0,0]
	ds_read_b128 v[246:249], v211 offset:8832
	ds_read_b128 v[250:253], v211 offset:8848
	s_waitcnt lgkmcnt(2)
	v_mfma_scale_f32_32x32x64_f8f6f4 v[230:245], v[40:47], v[24:31], v[230:245], v208, v208 op_sel_hi:[0,0,0]
	ds_read_b128 v[24:27], v211 offset:8896
	ds_read_b128 v[28:31], v211 offset:8912
	s_waitcnt lgkmcnt(2)
	v_mfma_scale_f32_32x32x64_f8f6f4 v[230:245], v[48:55], v[246:253], v[230:245], v208, v208 op_sel_hi:[0,0,0]
	ds_read_b128 v[246:249], v211 offset:8704
	ds_read_b128 v[250:253], v211 offset:8720
	s_waitcnt lgkmcnt(2)
	v_mfma_scale_f32_32x32x64_f8f6f4 v[230:245], v[56:63], v[24:31], v[230:245], v208, v208 op_sel_hi:[0,0,0]
	ds_read_b128 v[24:27], v211 offset:8768
	ds_read_b128 v[28:31], v211 offset:8784
	s_nop 15
	s_nop 1
	v_mul_f32_e32 v229, v231, v231
	v_fmac_f32_e32 v229, v230, v230
	v_fmac_f32_e32 v229, v232, v232
	v_fmac_f32_e32 v229, v233, v233
	v_fmac_f32_e32 v229, v234, v234
	v_fmac_f32_e32 v229, v235, v235
	v_fmac_f32_e32 v229, v236, v236
	v_fmac_f32_e32 v229, v237, v237
	v_fmac_f32_e32 v229, v238, v238
	v_fmac_f32_e32 v229, v239, v239
	v_fmac_f32_e32 v229, v240, v240
	v_fmac_f32_e32 v229, v241, v241
	v_fmac_f32_e32 v229, v242, v242
	v_fmac_f32_e32 v229, v243, v243
	v_fmac_f32_e32 v229, v244, v244
	v_fmac_f32_e32 v229, v245, v245
	s_waitcnt lgkmcnt(2)
	v_mfma_scale_f32_32x32x64_f8f6f4 v[230:245], v[64:71], v[246:253], 0, v208, v208 op_sel_hi:[0,0,0]
	ds_read_b128 v[246:249], v211 offset:8832
	ds_read_b128 v[250:253], v211 offset:8848
	s_waitcnt lgkmcnt(2)
	v_mfma_scale_f32_32x32x64_f8f6f4 v[230:245], v[72:79], v[24:31], v[230:245], v208, v208 op_sel_hi:[0,0,0]
	ds_read_b128 v[24:27], v211 offset:8896
	ds_read_b128 v[28:31], v211 offset:8912
	s_waitcnt lgkmcnt(2)
	v_mfma_scale_f32_32x32x64_f8f6f4 v[230:245], v[80:87], v[246:253], v[230:245], v208, v208 op_sel_hi:[0,0,0]
	s_waitcnt lgkmcnt(0)
	v_mfma_scale_f32_32x32x64_f8f6f4 v[230:245], v[88:95], v[24:31], v[230:245], v208, v208 op_sel_hi:[0,0,0]
	s_waitcnt vmcnt(9)
	v_cvt_pk_fp8_f32 v16, v136, v137
	v_cvt_pk_fp8_f32 v17, v148, v149
	v_cvt_pk_fp8_f32 v18, v160, v161
	v_cvt_pk_fp8_f32 v19, v144, v145
	v_cvt_pk_fp8_f32 v20, v156, v157
	v_cvt_pk_fp8_f32 v21, v140, v141
	v_cvt_pk_fp8_f32 v22, v152, v153
	v_cvt_pk_fp8_f32 v23, v164, v165
	v_cvt_pk_fp8_f32 v16, v138, v139 op_sel:[0,0,1]
	v_cvt_pk_fp8_f32 v17, v150, v151 op_sel:[0,0,1]
	v_cvt_pk_fp8_f32 v18, v162, v163 op_sel:[0,0,1]
	v_cvt_pk_fp8_f32 v19, v146, v147 op_sel:[0,0,1]
	v_cvt_pk_fp8_f32 v20, v158, v159 op_sel:[0,0,1]
	v_cvt_pk_fp8_f32 v21, v142, v143 op_sel:[0,0,1]
	v_cvt_pk_fp8_f32 v22, v154, v155 op_sel:[0,0,1]
	v_cvt_pk_fp8_f32 v23, v166, v167 op_sel:[0,0,1]
	s_nop 1
	ds_write_b32 v228, v16
	ds_write_b32 v228, v17 offset:2176
	ds_write_b32 v228, v18 offset:4352
	ds_write_b32 v228, v19 offset:6528
	ds_write_b32 v228, v20 offset:8704
	ds_write_b32 v228, v21 offset:10880
	ds_write_b32 v228, v22 offset:13056
	ds_write_b32 v228, v23 offset:15232
	v_fmac_f32_e32 v229, v230, v230
	v_fmac_f32_e32 v229, v231, v231
	v_fmac_f32_e32 v229, v232, v232
	v_fmac_f32_e32 v229, v233, v233
	v_fmac_f32_e32 v229, v234, v234
	v_fmac_f32_e32 v229, v235, v235
	v_fmac_f32_e32 v229, v236, v236
	v_fmac_f32_e32 v229, v237, v237
	v_fmac_f32_e32 v229, v238, v238
	v_fmac_f32_e32 v229, v239, v239
	v_fmac_f32_e32 v229, v240, v240
	v_fmac_f32_e32 v229, v241, v241
	v_fmac_f32_e32 v229, v242, v242
	v_fmac_f32_e32 v229, v243, v243
	v_fmac_f32_e32 v229, v244, v244
	v_fmac_f32_e32 v229, v245, v245
.LBB0_1613:
	s_waitcnt lgkmcnt(0)
	s_barrier
	ds_read_b128 v[238:241], v214 offset:38400
	ds_read_b128 v[242:245], v214 offset:38416
	ds_read_b128 v[246:249], v214 offset:57344
	ds_read_b128 v[250:253], v214 offset:57360
	ds_read_b128 v[16:19], v219
	ds_read_b64_tr_b16 v[20:21], v220
	ds_read_b64_tr_b16 v[22:23], v220 offset:2368
	ds_read_b128 v[24:27], v221
	ds_read_b64_tr_b16 v[28:29], v222
	ds_read_b64_tr_b16 v[30:31], v222 offset:2368
	ds_read_b128 v[230:233], v223
	ds_read_b64_tr_b16 v[234:235], v224
	ds_read_b64_tr_b16 v[236:237], v224 offset:2368
	s_waitcnt lgkmcnt(6)
	v_mfma_f32_32x32x16_bf16 v[0:15], v[16:19], v[20:23], v[0:15]
	ds_read_b128 v[16:19], v225
	ds_read_b64_tr_b16 v[20:21], v226
	ds_read_b64_tr_b16 v[22:23], v226 offset:2368
	s_waitcnt lgkmcnt(6)
	v_mfma_f32_32x32x16_bf16 v[0:15], v[24:27], v[28:31], v[0:15]
	v_lshlrev_b32_e32 v24, 16, v238
	v_and_b32_e32 v238, 0xffff0000, v238
	v_mul_f32_e32 v28, v238, v238
	v_fmac_f32_e32 v28, v24, v24
	v_lshlrev_b32_e32 v25, 16, v239
	v_and_b32_e32 v239, 0xffff0000, v239
	v_fmac_f32_e32 v28, v25, v25
	v_fmac_f32_e32 v28, v239, v239
	v_lshlrev_b32_e32 v26, 16, v240
	v_and_b32_e32 v240, 0xffff0000, v240
	v_fmac_f32_e32 v28, v26, v26
	v_fmac_f32_e32 v28, v240, v240
	v_lshlrev_b32_e32 v27, 16, v241
	v_and_b32_e32 v241, 0xffff0000, v241
	v_fmac_f32_e32 v28, v27, v27
	v_fmac_f32_e32 v28, v241, v241
	v_lshlrev_b32_e32 v24, 16, v242
	v_and_b32_e32 v242, 0xffff0000, v242
	v_fmac_f32_e32 v28, v24, v24
	v_fmac_f32_e32 v28, v242, v242
	v_lshlrev_b32_e32 v25, 16, v243
	v_and_b32_e32 v243, 0xffff0000, v243
	v_fmac_f32_e32 v28, v25, v25
	v_fmac_f32_e32 v28, v243, v243
	v_lshlrev_b32_e32 v26, 16, v244
	v_and_b32_e32 v244, 0xffff0000, v244
	v_fmac_f32_e32 v28, v26, v26
	v_fmac_f32_e32 v28, v244, v244
	v_lshlrev_b32_e32 v27, 16, v245
	v_and_b32_e32 v245, 0xffff0000, v245
	v_fmac_f32_e32 v28, v27, v27
	v_fmac_f32_e32 v28, v245, v245
	s_waitcnt lgkmcnt(3)
	v_mfma_f32_32x32x16_bf16 v[0:15], v[230:233], v[234:237], v[0:15]
	v_lshlrev_b32_e32 v24, 16, v246
	v_and_b32_e32 v246, 0xffff0000, v246
	v_mul_f32_e32 v29, v246, v246
	v_fmac_f32_e32 v29, v24, v24
	v_lshlrev_b32_e32 v25, 16, v247
	v_and_b32_e32 v247, 0xffff0000, v247
	v_fmac_f32_e32 v29, v25, v25
	v_fmac_f32_e32 v29, v247, v247
	v_lshlrev_b32_e32 v26, 16, v248
	v_and_b32_e32 v248, 0xffff0000, v248
	v_fmac_f32_e32 v29, v26, v26
	v_fmac_f32_e32 v29, v248, v248
	v_lshlrev_b32_e32 v27, 16, v249
	v_and_b32_e32 v249, 0xffff0000, v249
	v_fmac_f32_e32 v29, v27, v27
	v_fmac_f32_e32 v29, v249, v249
	v_lshlrev_b32_e32 v24, 16, v250
	v_and_b32_e32 v250, 0xffff0000, v250
	v_fmac_f32_e32 v29, v24, v24
	v_fmac_f32_e32 v29, v250, v250
	v_lshlrev_b32_e32 v25, 16, v251
	v_and_b32_e32 v251, 0xffff0000, v251
	v_fmac_f32_e32 v29, v25, v25
	v_fmac_f32_e32 v29, v251, v251
	v_lshlrev_b32_e32 v26, 16, v252
	v_and_b32_e32 v252, 0xffff0000, v252
	v_fmac_f32_e32 v29, v26, v26
	v_fmac_f32_e32 v29, v252, v252
	v_lshlrev_b32_e32 v27, 16, v253
	v_and_b32_e32 v253, 0xffff0000, v253
	v_fmac_f32_e32 v29, v27, v27
	v_fmac_f32_e32 v29, v253, v253
	s_waitcnt lgkmcnt(0)
	v_mfma_f32_32x32x16_bf16 v[0:15], v[16:19], v[20:23], v[0:15]
	v_fmac_f32_e32 v28, 0x3b800000, v180
	v_fmac_f32_e32 v29, 0x3b800000, v229
	v_mov_b32_e32 v16, v28
	v_mov_b32_e32 v17, v29
	ds_bpermute_b32 v19, v199, v16
	ds_bpermute_b32 v18, v199, v17
	s_waitcnt lgkmcnt(0)
	v_add_f32_e32 v16, v16, v19
	v_add_f32_e32 v17, v17, v18
	v_cndmask_b32_e64 v16, v17, v16, s[6:7]
	v_fmamk_f32 v16, v16, 0x3c2aaaab, v209
	v_mul_f32_e32 v19, 0x4f800000, v16
	v_cmp_gt_f32_e32 vcc, s37, v16
	s_nop 1
	v_cndmask_b32_e32 v16, v16, v19, vcc
	v_sqrt_f32_e32 v19, v16
	s_nop 0
	v_add_u32_e32 v20, -1, v19
	v_fma_f32 v22, -v20, v19, v16
	v_add_u32_e32 v21, 1, v19
	v_cmp_ge_f32_e64 s[0:1], 0, v22
	s_nop 1
	v_cndmask_b32_e64 v20, v19, v20, s[0:1]
	v_fma_f32 v19, -v21, v19, v16
	v_cmp_lt_f32_e64 s[0:1], 0, v19
	s_nop 1
	v_cndmask_b32_e64 v19, v20, v21, s[0:1]
	v_mul_f32_e32 v20, 0x37800000, v19
	v_cndmask_b32_e32 v19, v19, v20, vcc
	v_cmp_class_f32_e32 vcc, v16, v210
	s_nop 1
	v_cndmask_b32_e32 v16, v19, v16, vcc
	v_div_scale_f32 v19, s[0:1], v16, v16, 1.0
	v_rcp_f32_e32 v20, v19
	s_nop 0
	v_fma_f32 v18, -v19, v20, 1.0
	v_fmac_f32_e32 v20, v18, v20
	v_div_scale_f32 v18, vcc, 1.0, v16, 1.0
	v_mul_f32_e32 v21, v18, v20
	v_fma_f32 v23, -v19, v21, v18
	v_fmac_f32_e32 v21, v23, v20
	v_fma_f32 v18, -v19, v21, v18
	s_nop 0
	v_div_fmas_f32 v18, v18, v20, v21
	v_div_fixup_f32 v16, v18, v16, 1.0
	ds_write_b32 v203, v16
.LBB0_1615:
	s_waitcnt lgkmcnt(0)
	ds_read_b128 v[16:19], v215
	ds_read_b128 v[20:23], v216 offset:37888
	ds_read_b128 v[24:27], v215 offset:64
	ds_read_b128 v[28:31], v216 offset:37952
	ds_read_b128 v[230:233], v215 offset:512
	s_add_i32 s44, s42, 2
	s_waitcnt lgkmcnt(3)
	v_mfma_f32_16x16x32_bf16 v[16:19], v[16:19], v[20:23], 0
	ds_read_b128 v[20:23], v215 offset:128
	ds_read_b128 v[234:237], v216 offset:38016
	s_cmp_ge_u32 s44, s39
	s_cselect_b64 s[0:1], -1, 0
	s_waitcnt lgkmcnt(3)
	v_mfma_f32_16x16x32_bf16 v[16:19], v[24:27], v[28:31], v[16:19]
	ds_read_b128 v[24:27], v215 offset:192
	ds_read_b128 v[28:31], v216 offset:38080
	s_and_b64 vcc, exec, s[0:1]
	s_waitcnt lgkmcnt(2)
	v_mfma_f32_16x16x32_bf16 v[16:19], v[20:23], v[234:237], v[16:19]
	ds_read_b128 v[20:23], v215 offset:256
	ds_read_b128 v[234:237], v216 offset:38144
	s_waitcnt lgkmcnt(2)
	v_mfma_f32_16x16x32_bf16 v[16:19], v[24:27], v[28:31], v[16:19]
	ds_read_b128 v[24:27], v215 offset:320
	ds_read_b128 v[28:31], v216 offset:38208
	s_waitcnt lgkmcnt(2)
	v_mfma_f32_16x16x32_bf16 v[16:19], v[20:23], v[234:237], v[16:19]
	ds_read_b128 v[20:23], v215 offset:384
	ds_read_b128 v[234:237], v216 offset:38272
	s_waitcnt lgkmcnt(2)
	v_mfma_f32_16x16x32_bf16 v[16:19], v[24:27], v[28:31], v[16:19]
	ds_read_b128 v[24:27], v215 offset:448
	ds_read_b128 v[28:31], v216 offset:38336
	ds_read_b128 v[238:241], v216 offset:38400
	s_waitcnt lgkmcnt(0)
	s_barrier
	v_mfma_f32_16x16x32_bf16 v[16:19], v[20:23], v[234:237], v[16:19]
	ds_read_b32 v20, v217
	v_mfma_f32_16x16x32_bf16 v[16:19], v[24:27], v[28:31], v[16:19]
	v_mfma_f32_16x16x32_bf16 v[16:19], v[230:233], v[238:241], v[16:19]
	ds_read_b128 v[246:249], v207
	ds_read_b128 v[250:253], v207 offset:16
	ds_read_b128 v[24:27], v207 offset:64
	ds_read_b128 v[28:31], v207 offset:80
	s_waitcnt lgkmcnt(4)
	s_nop 6
	v_fma_f32 v16, v16, v20, -v177
	v_fma_f32 v17, v17, v20, -v177
	v_fma_f32 v18, v18, v20, -v177
	v_fma_f32 v19, v19, v20, -v177
	v_exp_f32_e32 v16, v16
	v_exp_f32_e32 v17, v17
	v_exp_f32_e32 v18, v18
	v_exp_f32_e32 v19, v19
	v_add_f32_e32 v188, v188, v192
	v_add_f32_e32 v189, v189, v193
	v_add_f32_e32 v186, v186, v190
	v_add_f32_e32 v187, v187, v191
	v_add_f32_e32 v188, v188, v16
	v_add_f32_e32 v189, v189, v17
	v_add_f32_e32 v186, v186, v18
	v_add_f32_e32 v187, v187, v19
	v_bfe_u32 v20, v16, 16, 1
	v_bfe_u32 v21, v17, 16, 1
	v_bfe_u32 v22, v18, 16, 1
	v_bfe_u32 v23, v19, 16, 1
	v_add3_u32 v20, v16, v20, s38
	v_add3_u32 v21, v17, v21, s38
	v_add3_u32 v22, v18, v22, s38
	v_add3_u32 v23, v19, v23, s38
	ds_write_b16_d16_hi v218, v20
	ds_write_b16_d16_hi v218, v21 offset:144
	ds_write_b16_d16_hi v218, v22 offset:288
	ds_write_b16_d16_hi v218, v23 offset:432
	s_cbranch_vccnz .LBB0_1618
	s_waitcnt lgkmcnt(6)
	v_mfma_scale_f32_32x32x64_f8f6f4 v[230:245], v[32:39], v[246:253], 0, v208, v208 op_sel_hi:[0,0,0]
	v_cvt_pk_bf16_f32 v16, v136, v137
	v_cvt_pk_bf16_f32 v17, v138, v139
	ds_write_b64 v201, v[16:17] offset:0
	v_cvt_pk_bf16_f32 v18, v148, v149
	v_cvt_pk_bf16_f32 v19, v150, v151
	ds_write_b64 v201, v[18:19] offset:4736
	v_cvt_pk_bf16_f32 v20, v160, v161
	v_cvt_pk_bf16_f32 v21, v162, v163
	ds_write_b64 v201, v[20:21] offset:9472
	v_cvt_pk_bf16_f32 v22, v144, v145
	v_cvt_pk_bf16_f32 v23, v146, v147
	ds_write_b64 v201, v[22:23] offset:14208
	ds_read_b128 v[246:249], v207 offset:128
	ds_read_b128 v[250:253], v207 offset:144
	s_waitcnt lgkmcnt(10)
	v_mfma_scale_f32_32x32x64_f8f6f4 v[230:245], v[40:47], v[24:31], v[230:245], v208, v208 op_sel_hi:[0,0,0]
	v_cvt_pk_bf16_f32 v16, v156, v157
	v_cvt_pk_bf16_f32 v17, v158, v159
	ds_write_b64 v201, v[16:17] offset:18944
	v_cvt_pk_bf16_f32 v18, v140, v141
	v_cvt_pk_bf16_f32 v19, v142, v143
	ds_write_b64 v201, v[18:19] offset:23680
	v_cvt_pk_bf16_f32 v20, v152, v153
	v_cvt_pk_bf16_f32 v21, v154, v155
	ds_write_b64 v201, v[20:21] offset:28416
	v_cvt_pk_bf16_f32 v22, v164, v165
	v_cvt_pk_bf16_f32 v23, v166, v167
	ds_write_b64 v201, v[22:23] offset:33152
	v_cvt_pk_bf16_f32 v16, v132, v133
	v_cvt_pk_bf16_f32 v17, v134, v135
	ds_write_b64 v213, v[16:17] offset:512
	ds_read_b128 v[24:27], v207 offset:192
	ds_read_b128 v[28:31], v207 offset:208
	s_waitcnt lgkmcnt(7)
	v_mfma_scale_f32_32x32x64_f8f6f4 v[230:245], v[48:55], v[246:253], v[230:245], v208, v208 op_sel_hi:[0,0,0]
	s_add_i32 s2, s41, 1
	v_readlane_b32 s2, v227, s2
	s_ashr_i32 s3, s2, 31
	s_lshl_b64 s[10:11], s[2:3], 17
	v_lshl_add_u64 v[16:17], v[182:183], 0, s[10:11]
	v_add_co_u32_e32 v18, vcc, 0x2000, v16
	s_lshl_b64 s[2:3], s[2:3], 14
	s_nop 0
	v_addc_co_u32_e32 v19, vcc, 0, v17, vcc
	global_load_dwordx4 v[136:139], v[16:17], off nt
	global_load_dwordx4 v[148:151], v[18:19], off nt
	v_add_co_u32_e32 v18, vcc, 0x4000, v16
	s_nop 1
	v_addc_co_u32_e32 v19, vcc, 0, v17, vcc
	v_add_co_u32_e32 v20, vcc, 0x6000, v16
	s_nop 1
	v_addc_co_u32_e32 v21, vcc, 0, v17, vcc
	global_load_dwordx4 v[160:163], v[18:19], off nt
	ds_read_b128 v[246:249], v207
	ds_read_b128 v[250:253], v207 offset:16
	s_waitcnt lgkmcnt(2)
	v_mfma_scale_f32_32x32x64_f8f6f4 v[230:245], v[56:63], v[24:31], v[230:245], v208, v208 op_sel_hi:[0,0,0]
	global_load_dwordx4 v[144:147], v[20:21], off nt
	v_add_co_u32_e32 v18, vcc, 0x8000, v16
	s_nop 1
	v_addc_co_u32_e32 v19, vcc, 0, v17, vcc
	v_add_co_u32_e32 v20, vcc, 0xa000, v16
	s_nop 1
	v_addc_co_u32_e32 v21, vcc, 0, v17, vcc
	global_load_dwordx4 v[156:159], v[18:19], off nt
	global_load_dwordx4 v[140:143], v[20:21], off nt
	v_add_co_u32_e32 v18, vcc, 0xc000, v16
	s_nop 1
	v_addc_co_u32_e32 v19, vcc, 0, v17, vcc
	v_add_co_u32_e32 v16, vcc, 0xe000, v16
	s_nop 1
	v_addc_co_u32_e32 v17, vcc, 0, v17, vcc
	global_load_dwordx4 v[152:155], v[18:19], off nt
	global_load_dwordx4 v[164:167], v[16:17], off nt
	v_lshl_add_u64 v[16:17], v[184:185], 0, s[2:3]
	global_load_dwordx4 v[132:135], v[16:17], off nt
	ds_read_b128 v[24:27], v207 offset:64
	ds_read_b128 v[28:31], v207 offset:80
	v_mul_f32_e32 v180, v231, v231
	v_fmac_f32_e32 v180, v230, v230
	v_fmac_f32_e32 v180, v232, v232
	v_fmac_f32_e32 v180, v233, v233
	v_fmac_f32_e32 v180, v234, v234
	v_fmac_f32_e32 v180, v235, v235
	v_fmac_f32_e32 v180, v236, v236
	v_fmac_f32_e32 v180, v237, v237
	v_fmac_f32_e32 v180, v238, v238
	v_fmac_f32_e32 v180, v239, v239
	v_fmac_f32_e32 v180, v240, v240
	v_fmac_f32_e32 v180, v241, v241
	v_fmac_f32_e32 v180, v242, v242
	v_fmac_f32_e32 v180, v243, v243
	v_fmac_f32_e32 v180, v244, v244
	v_fmac_f32_e32 v180, v245, v245
	s_waitcnt lgkmcnt(2)
	v_mfma_scale_f32_32x32x64_f8f6f4 v[230:245], v[64:71], v[246:253], 0, v208, v208 op_sel_hi:[0,0,0]
	ds_read_b128 v[246:249], v207 offset:128
	ds_read_b128 v[250:253], v207 offset:144
	s_waitcnt lgkmcnt(2)
	v_mfma_scale_f32_32x32x64_f8f6f4 v[230:245], v[72:79], v[24:31], v[230:245], v208, v208 op_sel_hi:[0,0,0]
	ds_read_b128 v[24:27], v207 offset:192
	ds_read_b128 v[28:31], v207 offset:208
	s_waitcnt lgkmcnt(2)
	v_mfma_scale_f32_32x32x64_f8f6f4 v[230:245], v[80:87], v[246:253], v[230:245], v208, v208 op_sel_hi:[0,0,0]
	ds_read_b128 v[246:249], v207 offset:8704
	ds_read_b128 v[250:253], v207 offset:8720
	s_waitcnt lgkmcnt(2)
	v_mfma_scale_f32_32x32x64_f8f6f4 v[230:245], v[88:95], v[24:31], v[230:245], v208, v208 op_sel_hi:[0,0,0]
	ds_read_b128 v[24:27], v207 offset:8768
	ds_read_b128 v[28:31], v207 offset:8784
	s_nop 15
	s_nop 1
	v_fmac_f32_e32 v180, v230, v230
	v_fmac_f32_e32 v180, v231, v231
	v_fmac_f32_e32 v180, v232, v232
	v_fmac_f32_e32 v180, v233, v233
	v_fmac_f32_e32 v180, v234, v234
	v_fmac_f32_e32 v180, v235, v235
	v_fmac_f32_e32 v180, v236, v236
	v_fmac_f32_e32 v180, v237, v237
	v_fmac_f32_e32 v180, v238, v238
	v_fmac_f32_e32 v180, v239, v239
	v_fmac_f32_e32 v180, v240, v240
	v_fmac_f32_e32 v180, v241, v241
	v_fmac_f32_e32 v180, v242, v242
	v_fmac_f32_e32 v180, v243, v243
	v_fmac_f32_e32 v180, v244, v244
	v_fmac_f32_e32 v180, v245, v245
	s_waitcnt lgkmcnt(2)
	v_mfma_scale_f32_32x32x64_f8f6f4 v[230:245], v[32:39], v[246:253], 0, v208, v208 op_sel_hi:[0,0,0]
	ds_read_b128 v[246:249], v207 offset:8832
	ds_read_b128 v[250:253], v207 offset:8848
	s_waitcnt lgkmcnt(2)
	v_mfma_scale_f32_32x32x64_f8f6f4 v[230:245], v[40:47], v[24:31], v[230:245], v208, v208 op_sel_hi:[0,0,0]
	ds_read_b128 v[24:27], v207 offset:8896
	ds_read_b128 v[28:31], v207 offset:8912
	s_waitcnt lgkmcnt(2)
	v_mfma_scale_f32_32x32x64_f8f6f4 v[230:245], v[48:55], v[246:253], v[230:245], v208, v208 op_sel_hi:[0,0,0]
	ds_read_b128 v[246:249], v207 offset:8704
	ds_read_b128 v[250:253], v207 offset:8720
	s_waitcnt lgkmcnt(2)
	v_mfma_scale_f32_32x32x64_f8f6f4 v[230:245], v[56:63], v[24:31], v[230:245], v208, v208 op_sel_hi:[0,0,0]
	ds_read_b128 v[24:27], v207 offset:8768
	ds_read_b128 v[28:31], v207 offset:8784
	s_nop 15
	s_nop 1
	v_mul_f32_e32 v229, v231, v231
	v_fmac_f32_e32 v229, v230, v230
	v_fmac_f32_e32 v229, v232, v232
	v_fmac_f32_e32 v229, v233, v233
	v_fmac_f32_e32 v229, v234, v234
	v_fmac_f32_e32 v229, v235, v235
	v_fmac_f32_e32 v229, v236, v236
	v_fmac_f32_e32 v229, v237, v237
	v_fmac_f32_e32 v229, v238, v238
	v_fmac_f32_e32 v229, v239, v239
	v_fmac_f32_e32 v229, v240, v240
	v_fmac_f32_e32 v229, v241, v241
	v_fmac_f32_e32 v229, v242, v242
	v_fmac_f32_e32 v229, v243, v243
	v_fmac_f32_e32 v229, v244, v244
	v_fmac_f32_e32 v229, v245, v245
	s_waitcnt lgkmcnt(2)
	v_mfma_scale_f32_32x32x64_f8f6f4 v[230:245], v[64:71], v[246:253], 0, v208, v208 op_sel_hi:[0,0,0]
	ds_read_b128 v[246:249], v207 offset:8832
	ds_read_b128 v[250:253], v207 offset:8848
	s_waitcnt lgkmcnt(2)
	v_mfma_scale_f32_32x32x64_f8f6f4 v[230:245], v[72:79], v[24:31], v[230:245], v208, v208 op_sel_hi:[0,0,0]
	ds_read_b128 v[24:27], v207 offset:8896
	ds_read_b128 v[28:31], v207 offset:8912
	s_waitcnt lgkmcnt(2)
	v_mfma_scale_f32_32x32x64_f8f6f4 v[230:245], v[80:87], v[246:253], v[230:245], v208, v208 op_sel_hi:[0,0,0]
	s_waitcnt lgkmcnt(0)
	v_mfma_scale_f32_32x32x64_f8f6f4 v[230:245], v[88:95], v[24:31], v[230:245], v208, v208 op_sel_hi:[0,0,0]
	s_waitcnt vmcnt(9)
	v_cvt_pk_fp8_f32 v16, v96, v97
	v_cvt_pk_fp8_f32 v17, v100, v101
	v_cvt_pk_fp8_f32 v18, v104, v105
	v_cvt_pk_fp8_f32 v19, v108, v109
	v_cvt_pk_fp8_f32 v20, v112, v113
	v_cvt_pk_fp8_f32 v21, v116, v117
	v_cvt_pk_fp8_f32 v22, v120, v121
	v_cvt_pk_fp8_f32 v23, v124, v125
	v_cvt_pk_fp8_f32 v16, v98, v99 op_sel:[0,0,1]
	v_cvt_pk_fp8_f32 v17, v102, v103 op_sel:[0,0,1]
	v_cvt_pk_fp8_f32 v18, v106, v107 op_sel:[0,0,1]
	v_cvt_pk_fp8_f32 v19, v110, v111 op_sel:[0,0,1]
	v_cvt_pk_fp8_f32 v20, v114, v115 op_sel:[0,0,1]
	v_cvt_pk_fp8_f32 v21, v118, v119 op_sel:[0,0,1]
	v_cvt_pk_fp8_f32 v22, v122, v123 op_sel:[0,0,1]
	v_cvt_pk_fp8_f32 v23, v126, v127 op_sel:[0,0,1]
	s_nop 1
	ds_write_b32 v228, v16 offset:17408
	ds_write_b32 v228, v17 offset:19584
	ds_write_b32 v228, v18 offset:21760
	ds_write_b32 v228, v19 offset:23936
	ds_write_b32 v228, v20 offset:26112
	ds_write_b32 v228, v21 offset:28288
	ds_write_b32 v228, v22 offset:30464
	ds_write_b32 v228, v23 offset:32640
	v_fmac_f32_e32 v229, v230, v230
	v_fmac_f32_e32 v229, v231, v231
	v_fmac_f32_e32 v229, v232, v232
	v_fmac_f32_e32 v229, v233, v233
	v_fmac_f32_e32 v229, v234, v234
	v_fmac_f32_e32 v229, v235, v235
	v_fmac_f32_e32 v229, v236, v236
	v_fmac_f32_e32 v229, v237, v237
	v_fmac_f32_e32 v229, v238, v238
	v_fmac_f32_e32 v229, v239, v239
	v_fmac_f32_e32 v229, v240, v240
	v_fmac_f32_e32 v229, v241, v241
	v_fmac_f32_e32 v229, v242, v242
	v_fmac_f32_e32 v229, v243, v243
	v_fmac_f32_e32 v229, v244, v244
	v_fmac_f32_e32 v229, v245, v245
.LBB0_1618:
	s_waitcnt lgkmcnt(0)
	s_barrier
	ds_read_b128 v[16:19], v219
	ds_read_b64_tr_b16 v[20:21], v220 offset:37888
	ds_read_b64_tr_b16 v[22:23], v220 offset:40256
	ds_read_b128 v[24:27], v221
	ds_read_b64_tr_b16 v[28:29], v222 offset:37888
	ds_read_b64_tr_b16 v[30:31], v222 offset:40256
	ds_read_b128 v[230:233], v223
	ds_read_b64_tr_b16 v[234:235], v224 offset:37888
	ds_read_b64_tr_b16 v[236:237], v224 offset:40256
	s_and_b32 s2, s43, 63
	s_cmp_eq_u32 s2, 63
	s_mov_b64 s[2:3], -1
	s_waitcnt lgkmcnt(6)
	v_mfma_f32_32x32x16_bf16 v[0:15], v[16:19], v[20:23], v[0:15]
	ds_read_b128 v[16:19], v225
	ds_read_b64_tr_b16 v[20:21], v226 offset:37888
	ds_read_b64_tr_b16 v[22:23], v226 offset:40256
	s_waitcnt lgkmcnt(6)
	v_mfma_f32_32x32x16_bf16 v[0:15], v[24:27], v[28:31], v[0:15]
	s_waitcnt lgkmcnt(3)
	v_mfma_f32_32x32x16_bf16 v[0:15], v[230:233], v[234:237], v[0:15]
	s_waitcnt lgkmcnt(0)
	v_mfma_f32_32x32x16_bf16 v[0:15], v[16:19], v[20:23], v[0:15]
	s_cbranch_scc0 .LBB0_1620
	s_andn2_b64 vcc, exec, s[2:3]
	s_cbranch_vccnz .LBB0_1601
	s_branch .LBB0_1621
